# P9 conv epilogue: no wait before the first conv when its weights were prefetched (avoids waiting for the k-loop's next-tile DMA loads)
# speedup vs baseline: 1.0011x; 1.0011x over previous
; __device__ __forceinline__ float dpp_ror1(float v) { return __int_as_float(__builtin_amdgcn_update_dpp(0, __float_as_int(v), 0x121, 0xf, 0xf, false)); }
; __device__ __forceinline__ float dpp_rol1(float v) { return __int_as_float(__builtin_amdgcn_update_dpp(0, __float_as_int(v), 0x12F, 0xf, 0xf, false)); }
;     __device__ __forceinline__ void tile(const f32x4 (&acc)[2][2][4][2], const Unit& u, int wr, int wc, int fr, int fq) const {
;     ...
;             const int cv = 128 * u.pn + 32 * wc + 16 * n + 4 * fq, cg = FF + cv;
;             const f32x4 wv0 = *(const f32x4*)(cw + cv), wv1 = *(const f32x4*)(cw + F2 + cv), wv2 = *(const f32x4*)(cw + 2 * F2 + cv), bv = *(const f32x4*)(cb + cv);
;             const f32x4 wg0 = *(const f32x4*)(cw + cg), wg1 = *(const f32x4*)(cw + F2 + cg), wg2 = *(const f32x4*)(cw + 2 * F2 + cg), bg = *(const f32x4*)(cb + cg);
; #pragma unroll
;             for (int ai = 0; ai < 2; ++ai)
; #pragma unroll
;                 for (int m = 0; m < 4; ++m) {
;                     f32x4 r;
; #pragma unroll
;                     for (int i = 0; i < 4; ++i) {
;                         const float xv = acc[ai][0][m][n][i], xg = acc[ai][1][m][n][i];
;                         const float uv = m > 0 ? acc[ai][0][m > 0 ? m - 1 : 0][n][i] : 0.f, ug = m > 0 ? acc[ai][1][m > 0 ? m - 1 : 0][n][i] : 0.f;
;                         const float dv = m < 3 ? acc[ai][0][m < 3 ? m + 1 : 3][n][i] : 0.f, dg = m < 3 ? acc[ai][1][m < 3 ? m + 1 : 3][n][i] : 0.f;
;                         const float pv = dpp_ror1(fr == 15 ? uv : xv), pg = dpp_ror1(fr == 15 ? ug : xg);
;                         const float nv = dpp_rol1(fr == 0 ? dv : xv), ng = dpp_rol1(fr == 0 ? dg : xg);
;                         const float yv = wv0[i] * pv + wv1[i] * xv + wv2[i] * nv + bv[i];
;                         const float yg = wg0[i] * pg + wg1[i] * xg + wg2[i] * ng + bg[i];
.Lp9c_havepre:
	global_load_dwordx4 v[120:123], v171, s[14:15]
	global_load_dwordx4 v[124:127], v171, s[58:59]
	global_load_dwordx4 v[128:131], v172, s[56:57] offset:64
	global_load_dwordx4 v[132:135], v172, s[12:13] offset:64
	global_load_dwordx4 v[136:139], v172, s[14:15] offset:64
	global_load_dwordx4 v[140:143], v172, s[58:59] offset:64
	global_load_dwordx4 v[144:147], v171, s[56:57] offset:64
	global_load_dwordx4 v[148:151], v171, s[12:13] offset:64
	global_load_dwordx4 v[208:211], v171, s[14:15] offset:64
	global_load_dwordx4 v[212:215], v171, s[58:59] offset:64
	s_lshl_b32 s17, s26, 8
	v_and_b32_e32 v173, 64, v195
	v_and_b32_e32 v174, 15, v195
	v_lshl_add_u32 v173, v174, 2, v173
	v_add_u32_e32 v173, s17, v173
	v_mul_u32_u24_e32 v173, 0x2c00, v173
	v_lshl_add_u32 v173, v170, 1, v173
	v_add_u32_e32 v174, 0x160000, v173
	s_cmp_lg_u32 s98, 0
	s_cbranch_scc1 .Lp9c_nowait
	s_waitcnt vmcnt(10)
.Lp9c_nowait:
	v_mov_b32_dpp v216, v96 row_shr:1 row_mask:0xf bank_mask:0xf bound_ctrl:1
	v_mov_b32_dpp v217, v97 row_shr:1 row_mask:0xf bank_mask:0xf bound_ctrl:1
	v_mov_b32_dpp v218, v98 row_shr:1 row_mask:0xf bank_mask:0xf bound_ctrl:1
	v_mov_b32_dpp v219, v99 row_shr:1 row_mask:0xf bank_mask:0xf bound_ctrl:1
	v_mov_b32_dpp v220, v152 row_shl:1 row_mask:0xf bank_mask:0xf bound_ctrl:1
	v_mov_b32_dpp v221, v153 row_shl:1 row_mask:0xf bank_mask:0xf bound_ctrl:1
	v_mov_b32_dpp v222, v154 row_shl:1 row_mask:0xf bank_mask:0xf bound_ctrl:1
	v_mov_b32_dpp v223, v155 row_shl:1 row_mask:0xf bank_mask:0xf bound_ctrl:1
	v_pk_mul_f32 v[176:177], v[152:153], v[234:235]
	v_pk_mul_f32 v[178:179], v[154:155], v[236:237]
	v_pk_mul_f32 v[180:181], v[112:113], v[234:235]
	v_pk_mul_f32 v[182:183], v[114:115], v[236:237]
	v_pk_mul_f32 v[184:185], v[104:105], v[234:235]
	v_pk_mul_f32 v[186:187], v[106:107], v[236:237]
	v_pk_mul_f32 v[224:225], v[96:97], v[234:235]
	v_pk_mul_f32 v[226:227], v[98:99], v[236:237]
	v_pk_fma_f32 v[176:177], v[230:231], v[216:217], v[176:177]
	v_pk_fma_f32 v[178:179], v[232:233], v[218:219], v[178:179]
	v_pk_fma_f32 v[180:181], v[230:231], v[152:153], v[180:181]
	v_pk_fma_f32 v[182:183], v[232:233], v[154:155], v[182:183]
	v_pk_fma_f32 v[184:185], v[230:231], v[112:113], v[184:185]
	v_pk_fma_f32 v[186:187], v[232:233], v[114:115], v[186:187]
	v_pk_fma_f32 v[224:225], v[230:231], v[104:105], v[224:225]
	v_pk_fma_f32 v[226:227], v[232:233], v[106:107], v[226:227]
	v_pk_fma_f32 v[176:177], v[238:239], v[112:113], v[176:177]
	v_pk_fma_f32 v[178:179], v[240:241], v[114:115], v[178:179]
	v_pk_fma_f32 v[180:181], v[238:239], v[104:105], v[180:181]
	v_pk_fma_f32 v[182:183], v[240:241], v[106:107], v[182:183]
	v_pk_fma_f32 v[184:185], v[238:239], v[96:97], v[184:185]
	v_pk_fma_f32 v[186:187], v[240:241], v[98:99], v[186:187]
	v_pk_fma_f32 v[224:225], v[238:239], v[220:221], v[224:225]
	v_pk_fma_f32 v[226:227], v[240:241], v[222:223], v[226:227]
	v_pk_add_f32 v[176:177], v[242:243], v[176:177]
	v_pk_add_f32 v[178:179], v[244:245], v[178:179]
	v_pk_add_f32 v[180:181], v[242:243], v[180:181]
	v_pk_add_f32 v[182:183], v[244:245], v[182:183]
	v_pk_add_f32 v[184:185], v[242:243], v[184:185]
	v_pk_add_f32 v[186:187], v[244:245], v[186:187]
	v_pk_add_f32 v[224:225], v[242:243], v[224:225]
	v_pk_add_f32 v[226:227], v[244:245], v[226:227]
	v_mov_b32_dpp v216, v100 row_shr:1 row_mask:0xf bank_mask:0xf bound_ctrl:1
	v_mov_b32_dpp v217, v101 row_shr:1 row_mask:0xf bank_mask:0xf bound_ctrl:1
	v_mov_b32_dpp v218, v102 row_shr:1 row_mask:0xf bank_mask:0xf bound_ctrl:1
	v_mov_b32_dpp v219, v103 row_shr:1 row_mask:0xf bank_mask:0xf bound_ctrl:1
	v_mov_b32_dpp v220, v156 row_shl:1 row_mask:0xf bank_mask:0xf bound_ctrl:1
	v_mov_b32_dpp v221, v157 row_shl:1 row_mask:0xf bank_mask:0xf bound_ctrl:1
	v_mov_b32_dpp v222, v158 row_shl:1 row_mask:0xf bank_mask:0xf bound_ctrl:1
	v_mov_b32_dpp v223, v159 row_shl:1 row_mask:0xf bank_mask:0xf bound_ctrl:1
	v_pk_mul_f32 v[152:153], v[156:157], v[250:251]
	v_pk_mul_f32 v[154:155], v[158:159], v[252:253]
	v_pk_mul_f32 v[112:113], v[116:117], v[250:251]
	v_pk_mul_f32 v[114:115], v[118:119], v[252:253]
	v_pk_mul_f32 v[104:105], v[108:109], v[250:251]
	v_pk_mul_f32 v[106:107], v[110:111], v[252:253]
	v_pk_mul_f32 v[96:97], v[100:101], v[250:251]
	v_pk_mul_f32 v[98:99], v[102:103], v[252:253]
	v_pk_fma_f32 v[152:153], v[246:247], v[216:217], v[152:153]
	v_pk_fma_f32 v[154:155], v[248:249], v[218:219], v[154:155]
	v_pk_fma_f32 v[112:113], v[246:247], v[156:157], v[112:113]
	v_pk_fma_f32 v[114:115], v[248:249], v[158:159], v[114:115]
	v_pk_fma_f32 v[104:105], v[246:247], v[116:117], v[104:105]
	v_pk_fma_f32 v[106:107], v[248:249], v[118:119], v[106:107]
	v_pk_fma_f32 v[96:97], v[246:247], v[108:109], v[96:97]
	v_pk_fma_f32 v[98:99], v[248:249], v[110:111], v[98:99]
	s_waitcnt vmcnt(8)
; __device__ __forceinline__ void st_bf4(bf16_t* p, f32x4 v) { u32x2 w; w.x = pk2(v[0], v[1]); w.y = pk2(v[2], v[3]); *(u32x2*)p = w; }
; __device__ __forceinline__ float sigmoidf_(float x) { return __builtin_amdgcn_rcpf(1.f + __expf(-x)); }
; __device__ __forceinline__ float dpp_ror1(float v) { return __int_as_float(__builtin_amdgcn_update_dpp(0, __float_as_int(v), 0x121, 0xf, 0xf, false)); }
; __device__ __forceinline__ float dpp_rol1(float v) { return __int_as_float(__builtin_amdgcn_update_dpp(0, __float_as_int(v), 0x12F, 0xf, 0xf, false)); }
;     __device__ __forceinline__ void tile(const f32x4 (&acc)[2][2][4][2], const Unit& u, int wr, int wc, int fr, int fq) const {
;     ...
;                     for (int i = 0; i < 4; ++i) {
;                         const float xv = acc[ai][0][m][n][i], xg = acc[ai][1][m][n][i];
;                         const float uv = m > 0 ? acc[ai][0][m > 0 ? m - 1 : 0][n][i] : 0.f, ug = m > 0 ? acc[ai][1][m > 0 ? m - 1 : 0][n][i] : 0.f;
;                         const float dv = m < 3 ? acc[ai][0][m < 3 ? m + 1 : 3][n][i] : 0.f, dg = m < 3 ? acc[ai][1][m < 3 ? m + 1 : 3][n][i] : 0.f;
;                         const float pv = dpp_ror1(fr == 15 ? uv : xv), pg = dpp_ror1(fr == 15 ? ug : xg);
;                         const float nv = dpp_rol1(fr == 0 ? dv : xv), ng = dpp_rol1(fr == 0 ? dg : xg);
;                         const float yv = wv0[i] * pv + wv1[i] * xv + wv2[i] * nv + bv[i];
;                         const float yg = wg0[i] * pg + wg1[i] * xg + wg2[i] * ng + bg[i];
;                         r[i] = yg * sigmoidf_(yg) * yv;
;                     }
;                     st_bf4(ACT + (size_t)(u.pm * BM + ai * HALF + wr * 64 + m * 16 + fr) * FF + cv, r);
	v_pk_fma_f32 v[152:153], v[120:121], v[116:117], v[152:153]
	v_pk_fma_f32 v[154:155], v[122:123], v[118:119], v[154:155]
	v_pk_fma_f32 v[112:113], v[120:121], v[108:109], v[112:113]
	v_pk_fma_f32 v[114:115], v[122:123], v[110:111], v[114:115]
	v_pk_fma_f32 v[104:105], v[120:121], v[100:101], v[104:105]
	v_pk_fma_f32 v[106:107], v[122:123], v[102:103], v[106:107]
	v_pk_fma_f32 v[96:97], v[120:121], v[220:221], v[96:97]
	v_pk_fma_f32 v[98:99], v[122:123], v[222:223], v[98:99]
	v_pk_add_f32 v[152:153], v[124:125], v[152:153]
	v_pk_add_f32 v[154:155], v[126:127], v[154:155]
	v_pk_add_f32 v[112:113], v[124:125], v[112:113]
	v_pk_add_f32 v[114:115], v[126:127], v[114:115]
	v_pk_add_f32 v[104:105], v[124:125], v[104:105]
	v_pk_add_f32 v[106:107], v[126:127], v[106:107]
	v_pk_add_f32 v[96:97], v[124:125], v[96:97]
	v_pk_add_f32 v[98:99], v[126:127], v[98:99]
	v_mul_f32_e32 v156, 0xbfb8aa3b, v176
	v_mul_f32_e32 v157, 0xbfb8aa3b, v177
	v_mul_f32_e32 v158, 0xbfb8aa3b, v178
	v_mul_f32_e32 v159, 0xbfb8aa3b, v179
	v_mul_f32_e32 v116, 0xbfb8aa3b, v180
	v_mul_f32_e32 v117, 0xbfb8aa3b, v181
	v_mul_f32_e32 v118, 0xbfb8aa3b, v182
	v_mul_f32_e32 v119, 0xbfb8aa3b, v183
	v_mul_f32_e32 v108, 0xbfb8aa3b, v184
	v_mul_f32_e32 v109, 0xbfb8aa3b, v185
	v_mul_f32_e32 v110, 0xbfb8aa3b, v186
	v_mul_f32_e32 v111, 0xbfb8aa3b, v187
	v_mul_f32_e32 v100, 0xbfb8aa3b, v224
	v_mul_f32_e32 v101, 0xbfb8aa3b, v225
	v_mul_f32_e32 v102, 0xbfb8aa3b, v226
	v_mul_f32_e32 v103, 0xbfb8aa3b, v227
	v_exp_f32_e32 v156, v156
	v_exp_f32_e32 v157, v157
	v_exp_f32_e32 v158, v158
	v_exp_f32_e32 v159, v159
	v_exp_f32_e32 v116, v116
	v_exp_f32_e32 v117, v117
	v_exp_f32_e32 v118, v118
	v_exp_f32_e32 v119, v119
	v_exp_f32_e32 v108, v108
	v_exp_f32_e32 v109, v109
	v_exp_f32_e32 v110, v110
	v_exp_f32_e32 v111, v111
	v_exp_f32_e32 v100, v100
	v_exp_f32_e32 v101, v101
	v_exp_f32_e32 v102, v102
	v_exp_f32_e32 v103, v103
	v_add_f32_e32 v156, 1.0, v156
	v_add_f32_e32 v157, 1.0, v157
	v_add_f32_e32 v158, 1.0, v158
	v_add_f32_e32 v159, 1.0, v159
	v_add_f32_e32 v116, 1.0, v116
	v_add_f32_e32 v117, 1.0, v117
	v_add_f32_e32 v118, 1.0, v118
	v_add_f32_e32 v119, 1.0, v119
	v_add_f32_e32 v108, 1.0, v108
	v_add_f32_e32 v109, 1.0, v109
	v_add_f32_e32 v110, 1.0, v110
	v_add_f32_e32 v111, 1.0, v111
	v_add_f32_e32 v100, 1.0, v100
	v_add_f32_e32 v101, 1.0, v101
	v_add_f32_e32 v102, 1.0, v102
	v_add_f32_e32 v103, 1.0, v103
	v_rcp_f32_e32 v156, v156
	v_rcp_f32_e32 v157, v157
	v_rcp_f32_e32 v158, v158
	v_rcp_f32_e32 v159, v159
	v_rcp_f32_e32 v116, v116
	v_rcp_f32_e32 v117, v117
	v_rcp_f32_e32 v118, v118
	v_rcp_f32_e32 v119, v119
	v_rcp_f32_e32 v108, v108
	v_rcp_f32_e32 v109, v109
	v_rcp_f32_e32 v110, v110
	v_rcp_f32_e32 v111, v111
	v_rcp_f32_e32 v100, v100
	v_rcp_f32_e32 v101, v101
	v_rcp_f32_e32 v102, v102
	v_rcp_f32_e32 v103, v103
	v_pk_mul_f32 v[176:177], v[176:177], v[156:157]
	v_pk_mul_f32 v[178:179], v[178:179], v[158:159]
	v_pk_mul_f32 v[180:181], v[180:181], v[116:117]
	v_pk_mul_f32 v[182:183], v[182:183], v[118:119]
	v_pk_mul_f32 v[184:185], v[184:185], v[108:109]
	v_pk_mul_f32 v[186:187], v[186:187], v[110:111]
	v_pk_mul_f32 v[224:225], v[224:225], v[100:101]
	v_pk_mul_f32 v[226:227], v[226:227], v[102:103]
	v_pk_mul_f32 v[176:177], v[152:153], v[176:177]
	v_pk_mul_f32 v[178:179], v[154:155], v[178:179]
	v_pk_mul_f32 v[180:181], v[112:113], v[180:181]
	v_pk_mul_f32 v[182:183], v[114:115], v[182:183]
	v_pk_mul_f32 v[184:185], v[104:105], v[184:185]
	v_pk_mul_f32 v[186:187], v[106:107], v[186:187]
	v_pk_mul_f32 v[224:225], v[96:97], v[224:225]
	v_pk_mul_f32 v[226:227], v[98:99], v[226:227]
	v_cvt_pk_bf16_f32 v156, v176, v177
	v_cvt_pk_bf16_f32 v157, v178, v179
	v_cvt_pk_bf16_f32 v116, v180, v181
	v_cvt_pk_bf16_f32 v117, v182, v183
	v_cvt_pk_bf16_f32 v108, v184, v185
	v_cvt_pk_bf16_f32 v109, v186, v187
	v_cvt_pk_bf16_f32 v100, v224, v225
	v_cvt_pk_bf16_f32 v101, v226, v227
	global_store_dwordx2 v173, v[156:157], s[0:1]
	v_add_u32_e32 v175, 0x2c00, v173
	global_store_dwordx2 v175, v[116:117], s[0:1]
	v_add_u32_e32 v175, 0x5800, v173
	global_store_dwordx2 v175, v[108:109], s[0:1]
	v_add_u32_e32 v175, 0x8400, v173
	global_store_dwordx2 v175, v[100:101], s[0:1]
	v_mov_b32_dpp v216, v64 row_shr:1 row_mask:0xf bank_mask:0xf bound_ctrl:1
	v_mov_b32_dpp v217, v65 row_shr:1 row_mask:0xf bank_mask:0xf bound_ctrl:1
	v_mov_b32_dpp v218, v66 row_shr:1 row_mask:0xf bank_mask:0xf bound_ctrl:1
	v_mov_b32_dpp v219, v67 row_shr:1 row_mask:0xf bank_mask:0xf bound_ctrl:1
	v_mov_b32_dpp v220, v88 row_shl:1 row_mask:0xf bank_mask:0xf bound_ctrl:1
	v_mov_b32_dpp v221, v89 row_shl:1 row_mask:0xf bank_mask:0xf bound_ctrl:1
	v_mov_b32_dpp v222, v90 row_shl:1 row_mask:0xf bank_mask:0xf bound_ctrl:1
	v_mov_b32_dpp v223, v91 row_shl:1 row_mask:0xf bank_mask:0xf bound_ctrl:1
	v_pk_mul_f32 v[176:177], v[88:89], v[234:235]
	v_pk_mul_f32 v[178:179], v[90:91], v[236:237]
	v_pk_mul_f32 v[180:181], v[80:81], v[234:235]
	v_pk_mul_f32 v[182:183], v[82:83], v[236:237]
	v_pk_mul_f32 v[184:185], v[72:73], v[234:235]
	v_pk_mul_f32 v[186:187], v[74:75], v[236:237]
	v_pk_mul_f32 v[224:225], v[64:65], v[234:235]
	v_pk_mul_f32 v[226:227], v[66:67], v[236:237]
	v_pk_fma_f32 v[176:177], v[230:231], v[216:217], v[176:177]
	v_pk_fma_f32 v[178:179], v[232:233], v[218:219], v[178:179]
	v_pk_fma_f32 v[180:181], v[230:231], v[88:89], v[180:181]
	v_pk_fma_f32 v[182:183], v[232:233], v[90:91], v[182:183]
	v_pk_fma_f32 v[184:185], v[230:231], v[80:81], v[184:185]
	v_pk_fma_f32 v[186:187], v[232:233], v[82:83], v[186:187]
	v_pk_fma_f32 v[224:225], v[230:231], v[72:73], v[224:225]
	v_pk_fma_f32 v[226:227], v[232:233], v[74:75], v[226:227]
	v_pk_fma_f32 v[176:177], v[238:239], v[80:81], v[176:177]
; __device__ __forceinline__ void st_bf4(bf16_t* p, f32x4 v) { u32x2 w; w.x = pk2(v[0], v[1]); w.y = pk2(v[2], v[3]); *(u32x2*)p = w; }
; __device__ __forceinline__ float sigmoidf_(float x) { return __builtin_amdgcn_rcpf(1.f + __expf(-x)); }
; __device__ __forceinline__ float dpp_ror1(float v) { return __int_as_float(__builtin_amdgcn_update_dpp(0, __float_as_int(v), 0x121, 0xf, 0xf, false)); }
; __device__ __forceinline__ float dpp_rol1(float v) { return __int_as_float(__builtin_amdgcn_update_dpp(0, __float_as_int(v), 0x12F, 0xf, 0xf, false)); }
;     __device__ __forceinline__ void tile(const f32x4 (&acc)[2][2][4][2], const Unit& u, int wr, int wc, int fr, int fq) const {
;     ...
;                     for (int i = 0; i < 4; ++i) {
;                         const float xv = acc[ai][0][m][n][i], xg = acc[ai][1][m][n][i];
;                         const float uv = m > 0 ? acc[ai][0][m > 0 ? m - 1 : 0][n][i] : 0.f, ug = m > 0 ? acc[ai][1][m > 0 ? m - 1 : 0][n][i] : 0.f;
;                         const float dv = m < 3 ? acc[ai][0][m < 3 ? m + 1 : 3][n][i] : 0.f, dg = m < 3 ? acc[ai][1][m < 3 ? m + 1 : 3][n][i] : 0.f;
;                         const float pv = dpp_ror1(fr == 15 ? uv : xv), pg = dpp_ror1(fr == 15 ? ug : xg);
;                         const float nv = dpp_rol1(fr == 0 ? dv : xv), ng = dpp_rol1(fr == 0 ? dg : xg);
;                         const float yv = wv0[i] * pv + wv1[i] * xv + wv2[i] * nv + bv[i];
;                         const float yg = wg0[i] * pg + wg1[i] * xg + wg2[i] * ng + bg[i];
;                         r[i] = yg * sigmoidf_(yg) * yv;
;                     }
;                     st_bf4(ACT + (size_t)(u.pm * BM + ai * HALF + wr * 64 + m * 16 + fr) * FF + cv, r);
	v_pk_fma_f32 v[178:179], v[240:241], v[82:83], v[178:179]
	v_pk_fma_f32 v[180:181], v[238:239], v[72:73], v[180:181]
	v_pk_fma_f32 v[182:183], v[240:241], v[74:75], v[182:183]
	v_pk_fma_f32 v[184:185], v[238:239], v[64:65], v[184:185]
	v_pk_fma_f32 v[186:187], v[240:241], v[66:67], v[186:187]
	v_pk_fma_f32 v[224:225], v[238:239], v[220:221], v[224:225]
	v_pk_fma_f32 v[226:227], v[240:241], v[222:223], v[226:227]
	v_pk_add_f32 v[176:177], v[242:243], v[176:177]
	v_pk_add_f32 v[178:179], v[244:245], v[178:179]
	v_pk_add_f32 v[180:181], v[242:243], v[180:181]
	v_pk_add_f32 v[182:183], v[244:245], v[182:183]
	v_pk_add_f32 v[184:185], v[242:243], v[184:185]
	v_pk_add_f32 v[186:187], v[244:245], v[186:187]
	v_pk_add_f32 v[224:225], v[242:243], v[224:225]
	v_pk_add_f32 v[226:227], v[244:245], v[226:227]
	v_mov_b32_dpp v216, v68 row_shr:1 row_mask:0xf bank_mask:0xf bound_ctrl:1
	v_mov_b32_dpp v217, v69 row_shr:1 row_mask:0xf bank_mask:0xf bound_ctrl:1
	v_mov_b32_dpp v218, v70 row_shr:1 row_mask:0xf bank_mask:0xf bound_ctrl:1
	v_mov_b32_dpp v219, v71 row_shr:1 row_mask:0xf bank_mask:0xf bound_ctrl:1
	v_mov_b32_dpp v220, v92 row_shl:1 row_mask:0xf bank_mask:0xf bound_ctrl:1
	v_mov_b32_dpp v221, v93 row_shl:1 row_mask:0xf bank_mask:0xf bound_ctrl:1
	v_mov_b32_dpp v222, v94 row_shl:1 row_mask:0xf bank_mask:0xf bound_ctrl:1
	v_mov_b32_dpp v223, v95 row_shl:1 row_mask:0xf bank_mask:0xf bound_ctrl:1
	v_pk_mul_f32 v[88:89], v[92:93], v[250:251]
	v_pk_mul_f32 v[90:91], v[94:95], v[252:253]
	v_pk_mul_f32 v[80:81], v[84:85], v[250:251]
	v_pk_mul_f32 v[82:83], v[86:87], v[252:253]
	v_pk_mul_f32 v[72:73], v[76:77], v[250:251]
	v_pk_mul_f32 v[74:75], v[78:79], v[252:253]
	v_pk_mul_f32 v[64:65], v[68:69], v[250:251]
	v_pk_mul_f32 v[66:67], v[70:71], v[252:253]
	v_pk_fma_f32 v[88:89], v[246:247], v[216:217], v[88:89]
	v_pk_fma_f32 v[90:91], v[248:249], v[218:219], v[90:91]
	v_pk_fma_f32 v[80:81], v[246:247], v[92:93], v[80:81]
	v_pk_fma_f32 v[82:83], v[248:249], v[94:95], v[82:83]
	v_pk_fma_f32 v[72:73], v[246:247], v[84:85], v[72:73]
	v_pk_fma_f32 v[74:75], v[248:249], v[86:87], v[74:75]
	v_pk_fma_f32 v[64:65], v[246:247], v[76:77], v[64:65]
	v_pk_fma_f32 v[66:67], v[248:249], v[78:79], v[66:67]
	v_pk_fma_f32 v[88:89], v[120:121], v[84:85], v[88:89]
	v_pk_fma_f32 v[90:91], v[122:123], v[86:87], v[90:91]
	v_pk_fma_f32 v[80:81], v[120:121], v[76:77], v[80:81]
	v_pk_fma_f32 v[82:83], v[122:123], v[78:79], v[82:83]
	v_pk_fma_f32 v[72:73], v[120:121], v[68:69], v[72:73]
	v_pk_fma_f32 v[74:75], v[122:123], v[70:71], v[74:75]
	v_pk_fma_f32 v[64:65], v[120:121], v[220:221], v[64:65]
	v_pk_fma_f32 v[66:67], v[122:123], v[222:223], v[66:67]
	v_pk_add_f32 v[88:89], v[124:125], v[88:89]
	v_pk_add_f32 v[90:91], v[126:127], v[90:91]
	v_pk_add_f32 v[80:81], v[124:125], v[80:81]
	v_pk_add_f32 v[82:83], v[126:127], v[82:83]
	v_pk_add_f32 v[72:73], v[124:125], v[72:73]
	v_pk_add_f32 v[74:75], v[126:127], v[74:75]
	v_pk_add_f32 v[64:65], v[124:125], v[64:65]
	v_pk_add_f32 v[66:67], v[126:127], v[66:67]
	v_mul_f32_e32 v92, 0xbfb8aa3b, v176
	v_mul_f32_e32 v93, 0xbfb8aa3b, v177
	v_mul_f32_e32 v94, 0xbfb8aa3b, v178
	v_mul_f32_e32 v95, 0xbfb8aa3b, v179
	v_mul_f32_e32 v84, 0xbfb8aa3b, v180
	v_mul_f32_e32 v85, 0xbfb8aa3b, v181
	v_mul_f32_e32 v86, 0xbfb8aa3b, v182
	v_mul_f32_e32 v87, 0xbfb8aa3b, v183
	v_mul_f32_e32 v76, 0xbfb8aa3b, v184
	v_mul_f32_e32 v77, 0xbfb8aa3b, v185
	v_mul_f32_e32 v78, 0xbfb8aa3b, v186
	v_mul_f32_e32 v79, 0xbfb8aa3b, v187
	v_mul_f32_e32 v68, 0xbfb8aa3b, v224
	v_mul_f32_e32 v69, 0xbfb8aa3b, v225
	v_mul_f32_e32 v70, 0xbfb8aa3b, v226
	v_mul_f32_e32 v71, 0xbfb8aa3b, v227
	v_exp_f32_e32 v92, v92
	v_exp_f32_e32 v93, v93
	v_exp_f32_e32 v94, v94
	v_exp_f32_e32 v95, v95
	v_exp_f32_e32 v84, v84
	v_exp_f32_e32 v85, v85
	v_exp_f32_e32 v86, v86
	v_exp_f32_e32 v87, v87
	v_exp_f32_e32 v76, v76
	v_exp_f32_e32 v77, v77
	v_exp_f32_e32 v78, v78
	v_exp_f32_e32 v79, v79
	v_exp_f32_e32 v68, v68
	v_exp_f32_e32 v69, v69
	v_exp_f32_e32 v70, v70
	v_exp_f32_e32 v71, v71
	v_add_f32_e32 v92, 1.0, v92
	v_add_f32_e32 v93, 1.0, v93
	v_add_f32_e32 v94, 1.0, v94
	v_add_f32_e32 v95, 1.0, v95
	v_add_f32_e32 v84, 1.0, v84
	v_add_f32_e32 v85, 1.0, v85
	v_add_f32_e32 v86, 1.0, v86
	v_add_f32_e32 v87, 1.0, v87
	v_add_f32_e32 v76, 1.0, v76
	v_add_f32_e32 v77, 1.0, v77
	v_add_f32_e32 v78, 1.0, v78
	v_add_f32_e32 v79, 1.0, v79
	v_add_f32_e32 v68, 1.0, v68
	v_add_f32_e32 v69, 1.0, v69
	v_add_f32_e32 v70, 1.0, v70
	v_add_f32_e32 v71, 1.0, v71
	v_rcp_f32_e32 v92, v92
	v_rcp_f32_e32 v93, v93
	v_rcp_f32_e32 v94, v94
	v_rcp_f32_e32 v95, v95
	v_rcp_f32_e32 v84, v84
	v_rcp_f32_e32 v85, v85
	v_rcp_f32_e32 v86, v86
	v_rcp_f32_e32 v87, v87
	v_rcp_f32_e32 v76, v76
	v_rcp_f32_e32 v77, v77
	v_rcp_f32_e32 v78, v78
	v_rcp_f32_e32 v79, v79
	v_rcp_f32_e32 v68, v68
	v_rcp_f32_e32 v69, v69
	v_rcp_f32_e32 v70, v70
	v_rcp_f32_e32 v71, v71
	v_pk_mul_f32 v[176:177], v[176:177], v[92:93]
	v_pk_mul_f32 v[178:179], v[178:179], v[94:95]
	v_pk_mul_f32 v[180:181], v[180:181], v[84:85]
	v_pk_mul_f32 v[182:183], v[182:183], v[86:87]
	v_pk_mul_f32 v[184:185], v[184:185], v[76:77]
	v_pk_mul_f32 v[186:187], v[186:187], v[78:79]
	v_pk_mul_f32 v[224:225], v[224:225], v[68:69]
	v_pk_mul_f32 v[226:227], v[226:227], v[70:71]
	v_pk_mul_f32 v[176:177], v[88:89], v[176:177]
	v_pk_mul_f32 v[178:179], v[90:91], v[178:179]
	v_pk_mul_f32 v[180:181], v[80:81], v[180:181]
	v_pk_mul_f32 v[182:183], v[82:83], v[182:183]
	v_pk_mul_f32 v[184:185], v[72:73], v[184:185]
	v_pk_mul_f32 v[186:187], v[74:75], v[186:187]
	v_pk_mul_f32 v[224:225], v[64:65], v[224:225]
	v_pk_mul_f32 v[226:227], v[66:67], v[226:227]
	v_cvt_pk_bf16_f32 v92, v176, v177
	v_cvt_pk_bf16_f32 v93, v178, v179
	v_cvt_pk_bf16_f32 v84, v180, v181
	v_cvt_pk_bf16_f32 v85, v182, v183
	v_cvt_pk_bf16_f32 v76, v184, v185
	v_cvt_pk_bf16_f32 v77, v186, v187
	v_cvt_pk_bf16_f32 v68, v224, v225
	v_cvt_pk_bf16_f32 v69, v226, v227
	global_store_dwordx2 v174, v[92:93], s[0:1]
	v_add_u32_e32 v175, 0x2c00, v174
	global_store_dwordx2 v175, v[84:85], s[0:1]
	v_add_u32_e32 v175, 0x5800, v174
	global_store_dwordx2 v175, v[76:77], s[0:1]
	v_add_u32_e32 v175, 0x8400, v174
	global_store_dwordx2 v175, v[68:69], s[0:1]
	s_waitcnt vmcnt(12)
; __device__ __forceinline__ float sigmoidf_(float x) { return __builtin_amdgcn_rcpf(1.f + __expf(-x)); }
; __device__ __forceinline__ float dpp_ror1(float v) { return __int_as_float(__builtin_amdgcn_update_dpp(0, __float_as_int(v), 0x121, 0xf, 0xf, false)); }
; __device__ __forceinline__ float dpp_rol1(float v) { return __int_as_float(__builtin_amdgcn_update_dpp(0, __float_as_int(v), 0x12F, 0xf, 0xf, false)); }
;     __device__ __forceinline__ void tile(const f32x4 (&acc)[2][2][4][2], const Unit& u, int wr, int wc, int fr, int fq) const {
;     ...
;                     for (int i = 0; i < 4; ++i) {
;                         const float xv = acc[ai][0][m][n][i], xg = acc[ai][1][m][n][i];
;                         const float uv = m > 0 ? acc[ai][0][m > 0 ? m - 1 : 0][n][i] : 0.f, ug = m > 0 ? acc[ai][1][m > 0 ? m - 1 : 0][n][i] : 0.f;
;                         const float dv = m < 3 ? acc[ai][0][m < 3 ? m + 1 : 3][n][i] : 0.f, dg = m < 3 ? acc[ai][1][m < 3 ? m + 1 : 3][n][i] : 0.f;
;                         const float pv = dpp_ror1(fr == 15 ? uv : xv), pg = dpp_ror1(fr == 15 ? ug : xg);
;                         const float nv = dpp_rol1(fr == 0 ? dv : xv), ng = dpp_rol1(fr == 0 ? dg : xg);
;                         const float yv = wv0[i] * pv + wv1[i] * xv + wv2[i] * nv + bv[i];
;                         const float yg = wg0[i] * pg + wg1[i] * xg + wg2[i] * ng + bg[i];
;                         r[i] = yg * sigmoidf_(yg) * yv;
	v_mov_b32_dpp v216, v32 row_shr:1 row_mask:0xf bank_mask:0xf bound_ctrl:1
	v_mov_b32_dpp v217, v33 row_shr:1 row_mask:0xf bank_mask:0xf bound_ctrl:1
	v_mov_b32_dpp v218, v34 row_shr:1 row_mask:0xf bank_mask:0xf bound_ctrl:1
	v_mov_b32_dpp v219, v35 row_shr:1 row_mask:0xf bank_mask:0xf bound_ctrl:1
	v_mov_b32_dpp v220, v56 row_shl:1 row_mask:0xf bank_mask:0xf bound_ctrl:1
	v_mov_b32_dpp v221, v57 row_shl:1 row_mask:0xf bank_mask:0xf bound_ctrl:1
	v_mov_b32_dpp v222, v58 row_shl:1 row_mask:0xf bank_mask:0xf bound_ctrl:1
	v_mov_b32_dpp v223, v59 row_shl:1 row_mask:0xf bank_mask:0xf bound_ctrl:1
	v_pk_mul_f32 v[176:177], v[56:57], v[132:133]
	v_pk_mul_f32 v[178:179], v[58:59], v[134:135]
	v_pk_mul_f32 v[180:181], v[48:49], v[132:133]
	v_pk_mul_f32 v[182:183], v[50:51], v[134:135]
	v_pk_mul_f32 v[184:185], v[40:41], v[132:133]
	v_pk_mul_f32 v[186:187], v[42:43], v[134:135]
	v_pk_mul_f32 v[224:225], v[32:33], v[132:133]
	v_pk_mul_f32 v[226:227], v[34:35], v[134:135]
	v_pk_fma_f32 v[176:177], v[128:129], v[216:217], v[176:177]
	v_pk_fma_f32 v[178:179], v[130:131], v[218:219], v[178:179]
	v_pk_fma_f32 v[180:181], v[128:129], v[56:57], v[180:181]
	v_pk_fma_f32 v[182:183], v[130:131], v[58:59], v[182:183]
	v_pk_fma_f32 v[184:185], v[128:129], v[48:49], v[184:185]
	v_pk_fma_f32 v[186:187], v[130:131], v[50:51], v[186:187]
	v_pk_fma_f32 v[224:225], v[128:129], v[40:41], v[224:225]
	v_pk_fma_f32 v[226:227], v[130:131], v[42:43], v[226:227]
	v_pk_fma_f32 v[176:177], v[136:137], v[48:49], v[176:177]
	v_pk_fma_f32 v[178:179], v[138:139], v[50:51], v[178:179]
	v_pk_fma_f32 v[180:181], v[136:137], v[40:41], v[180:181]
	v_pk_fma_f32 v[182:183], v[138:139], v[42:43], v[182:183]
	v_pk_fma_f32 v[184:185], v[136:137], v[32:33], v[184:185]
	v_pk_fma_f32 v[186:187], v[138:139], v[34:35], v[186:187]
	v_pk_fma_f32 v[224:225], v[136:137], v[220:221], v[224:225]
	v_pk_fma_f32 v[226:227], v[138:139], v[222:223], v[226:227]
	v_pk_add_f32 v[176:177], v[140:141], v[176:177]
	v_pk_add_f32 v[178:179], v[142:143], v[178:179]
	v_pk_add_f32 v[180:181], v[140:141], v[180:181]
	v_pk_add_f32 v[182:183], v[142:143], v[182:183]
	v_pk_add_f32 v[184:185], v[140:141], v[184:185]
	v_pk_add_f32 v[186:187], v[142:143], v[186:187]
	v_pk_add_f32 v[224:225], v[140:141], v[224:225]
	v_pk_add_f32 v[226:227], v[142:143], v[226:227]
	s_waitcnt vmcnt(8)
	v_mov_b32_dpp v216, v36 row_shr:1 row_mask:0xf bank_mask:0xf bound_ctrl:1
	v_mov_b32_dpp v217, v37 row_shr:1 row_mask:0xf bank_mask:0xf bound_ctrl:1
	v_mov_b32_dpp v218, v38 row_shr:1 row_mask:0xf bank_mask:0xf bound_ctrl:1
	v_mov_b32_dpp v219, v39 row_shr:1 row_mask:0xf bank_mask:0xf bound_ctrl:1
	v_mov_b32_dpp v220, v60 row_shl:1 row_mask:0xf bank_mask:0xf bound_ctrl:1
	v_mov_b32_dpp v221, v61 row_shl:1 row_mask:0xf bank_mask:0xf bound_ctrl:1
	v_mov_b32_dpp v222, v62 row_shl:1 row_mask:0xf bank_mask:0xf bound_ctrl:1
	v_mov_b32_dpp v223, v63 row_shl:1 row_mask:0xf bank_mask:0xf bound_ctrl:1
	v_pk_mul_f32 v[56:57], v[60:61], v[148:149]
	v_pk_mul_f32 v[58:59], v[62:63], v[150:151]
	v_pk_mul_f32 v[48:49], v[52:53], v[148:149]
	v_pk_mul_f32 v[50:51], v[54:55], v[150:151]
	v_pk_mul_f32 v[40:41], v[44:45], v[148:149]
	v_pk_mul_f32 v[42:43], v[46:47], v[150:151]
	v_pk_mul_f32 v[32:33], v[36:37], v[148:149]
	v_pk_mul_f32 v[34:35], v[38:39], v[150:151]
	v_pk_fma_f32 v[56:57], v[144:145], v[216:217], v[56:57]
	v_pk_fma_f32 v[58:59], v[146:147], v[218:219], v[58:59]
	v_pk_fma_f32 v[48:49], v[144:145], v[60:61], v[48:49]
	v_pk_fma_f32 v[50:51], v[146:147], v[62:63], v[50:51]
	v_pk_fma_f32 v[40:41], v[144:145], v[52:53], v[40:41]
	v_pk_fma_f32 v[42:43], v[146:147], v[54:55], v[42:43]
	v_pk_fma_f32 v[32:33], v[144:145], v[44:45], v[32:33]
	v_pk_fma_f32 v[34:35], v[146:147], v[46:47], v[34:35]
	v_pk_fma_f32 v[56:57], v[208:209], v[52:53], v[56:57]
	v_pk_fma_f32 v[58:59], v[210:211], v[54:55], v[58:59]
	v_pk_fma_f32 v[48:49], v[208:209], v[44:45], v[48:49]
	v_pk_fma_f32 v[50:51], v[210:211], v[46:47], v[50:51]
	v_pk_fma_f32 v[40:41], v[208:209], v[36:37], v[40:41]
	v_pk_fma_f32 v[42:43], v[210:211], v[38:39], v[42:43]
	v_pk_fma_f32 v[32:33], v[208:209], v[220:221], v[32:33]
	v_pk_fma_f32 v[34:35], v[210:211], v[222:223], v[34:35]
	v_pk_add_f32 v[56:57], v[212:213], v[56:57]
	v_pk_add_f32 v[58:59], v[214:215], v[58:59]
	v_pk_add_f32 v[48:49], v[212:213], v[48:49]
	v_pk_add_f32 v[50:51], v[214:215], v[50:51]
	v_pk_add_f32 v[40:41], v[212:213], v[40:41]
	v_pk_add_f32 v[42:43], v[214:215], v[42:43]
	v_pk_add_f32 v[32:33], v[212:213], v[32:33]
	v_pk_add_f32 v[34:35], v[214:215], v[34:35]
	v_mul_f32_e32 v60, 0xbfb8aa3b, v176
	v_mul_f32_e32 v61, 0xbfb8aa3b, v177
	v_mul_f32_e32 v62, 0xbfb8aa3b, v178
	v_mul_f32_e32 v63, 0xbfb8aa3b, v179
	v_mul_f32_e32 v52, 0xbfb8aa3b, v180
	v_mul_f32_e32 v53, 0xbfb8aa3b, v181
	v_mul_f32_e32 v54, 0xbfb8aa3b, v182
	v_mul_f32_e32 v55, 0xbfb8aa3b, v183
	v_mul_f32_e32 v44, 0xbfb8aa3b, v184
	v_mul_f32_e32 v45, 0xbfb8aa3b, v185
	v_mul_f32_e32 v46, 0xbfb8aa3b, v186
	v_mul_f32_e32 v47, 0xbfb8aa3b, v187
	v_mul_f32_e32 v36, 0xbfb8aa3b, v224
	v_mul_f32_e32 v37, 0xbfb8aa3b, v225
	v_mul_f32_e32 v38, 0xbfb8aa3b, v226
	v_mul_f32_e32 v39, 0xbfb8aa3b, v227
	v_exp_f32_e32 v60, v60
	v_exp_f32_e32 v61, v61
	v_exp_f32_e32 v62, v62
	v_exp_f32_e32 v63, v63
	v_exp_f32_e32 v52, v52
	v_exp_f32_e32 v53, v53
	v_exp_f32_e32 v54, v54
	v_exp_f32_e32 v55, v55
	v_exp_f32_e32 v44, v44
	v_exp_f32_e32 v45, v45
	v_exp_f32_e32 v46, v46
	v_exp_f32_e32 v47, v47
	v_exp_f32_e32 v36, v36
	v_exp_f32_e32 v37, v37
	v_exp_f32_e32 v38, v38
	v_exp_f32_e32 v39, v39
	v_add_f32_e32 v60, 1.0, v60
	v_add_f32_e32 v61, 1.0, v61
	v_add_f32_e32 v62, 1.0, v62
	v_add_f32_e32 v63, 1.0, v63
; __device__ __forceinline__ void st_bf4(bf16_t* p, f32x4 v) { u32x2 w; w.x = pk2(v[0], v[1]); w.y = pk2(v[2], v[3]); *(u32x2*)p = w; }
; __device__ __forceinline__ float sigmoidf_(float x) { return __builtin_amdgcn_rcpf(1.f + __expf(-x)); }
; __device__ __forceinline__ float dpp_ror1(float v) { return __int_as_float(__builtin_amdgcn_update_dpp(0, __float_as_int(v), 0x121, 0xf, 0xf, false)); }
; __device__ __forceinline__ float dpp_rol1(float v) { return __int_as_float(__builtin_amdgcn_update_dpp(0, __float_as_int(v), 0x12F, 0xf, 0xf, false)); }
;     __device__ __forceinline__ void tile(const f32x4 (&acc)[2][2][4][2], const Unit& u, int wr, int wc, int fr, int fq) const {
;     ...
;                     for (int i = 0; i < 4; ++i) {
;                         const float xv = acc[ai][0][m][n][i], xg = acc[ai][1][m][n][i];
;                         const float uv = m > 0 ? acc[ai][0][m > 0 ? m - 1 : 0][n][i] : 0.f, ug = m > 0 ? acc[ai][1][m > 0 ? m - 1 : 0][n][i] : 0.f;
;                         const float dv = m < 3 ? acc[ai][0][m < 3 ? m + 1 : 3][n][i] : 0.f, dg = m < 3 ? acc[ai][1][m < 3 ? m + 1 : 3][n][i] : 0.f;
;                         const float pv = dpp_ror1(fr == 15 ? uv : xv), pg = dpp_ror1(fr == 15 ? ug : xg);
;                         const float nv = dpp_rol1(fr == 0 ? dv : xv), ng = dpp_rol1(fr == 0 ? dg : xg);
;                         const float yv = wv0[i] * pv + wv1[i] * xv + wv2[i] * nv + bv[i];
;                         const float yg = wg0[i] * pg + wg1[i] * xg + wg2[i] * ng + bg[i];
;                         r[i] = yg * sigmoidf_(yg) * yv;
;                     }
;                     st_bf4(ACT + (size_t)(u.pm * BM + ai * HALF + wr * 64 + m * 16 + fr) * FF + cv, r);
	v_add_f32_e32 v52, 1.0, v52
	v_add_f32_e32 v53, 1.0, v53
	v_add_f32_e32 v54, 1.0, v54
	v_add_f32_e32 v55, 1.0, v55
	v_add_f32_e32 v44, 1.0, v44
	v_add_f32_e32 v45, 1.0, v45
	v_add_f32_e32 v46, 1.0, v46
	v_add_f32_e32 v47, 1.0, v47
	v_add_f32_e32 v36, 1.0, v36
	v_add_f32_e32 v37, 1.0, v37
	v_add_f32_e32 v38, 1.0, v38
	v_add_f32_e32 v39, 1.0, v39
	v_rcp_f32_e32 v60, v60
	v_rcp_f32_e32 v61, v61
	v_rcp_f32_e32 v62, v62
	v_rcp_f32_e32 v63, v63
	v_rcp_f32_e32 v52, v52
	v_rcp_f32_e32 v53, v53
	v_rcp_f32_e32 v54, v54
	v_rcp_f32_e32 v55, v55
	v_rcp_f32_e32 v44, v44
	v_rcp_f32_e32 v45, v45
	v_rcp_f32_e32 v46, v46
	v_rcp_f32_e32 v47, v47
	v_rcp_f32_e32 v36, v36
	v_rcp_f32_e32 v37, v37
	v_rcp_f32_e32 v38, v38
	v_rcp_f32_e32 v39, v39
	v_pk_mul_f32 v[176:177], v[176:177], v[60:61]
	v_pk_mul_f32 v[178:179], v[178:179], v[62:63]
	v_pk_mul_f32 v[180:181], v[180:181], v[52:53]
	v_pk_mul_f32 v[182:183], v[182:183], v[54:55]
	v_pk_mul_f32 v[184:185], v[184:185], v[44:45]
	v_pk_mul_f32 v[186:187], v[186:187], v[46:47]
	v_pk_mul_f32 v[224:225], v[224:225], v[36:37]
	v_pk_mul_f32 v[226:227], v[226:227], v[38:39]
	v_pk_mul_f32 v[176:177], v[56:57], v[176:177]
	v_pk_mul_f32 v[178:179], v[58:59], v[178:179]
	v_pk_mul_f32 v[180:181], v[48:49], v[180:181]
	v_pk_mul_f32 v[182:183], v[50:51], v[182:183]
	v_pk_mul_f32 v[184:185], v[40:41], v[184:185]
	v_pk_mul_f32 v[186:187], v[42:43], v[186:187]
	v_pk_mul_f32 v[224:225], v[32:33], v[224:225]
	v_pk_mul_f32 v[226:227], v[34:35], v[226:227]
	v_cvt_pk_bf16_f32 v60, v176, v177
	v_cvt_pk_bf16_f32 v61, v178, v179
	v_cvt_pk_bf16_f32 v52, v180, v181
	v_cvt_pk_bf16_f32 v53, v182, v183
	v_cvt_pk_bf16_f32 v44, v184, v185
	v_cvt_pk_bf16_f32 v45, v186, v187
	v_cvt_pk_bf16_f32 v36, v224, v225
	v_cvt_pk_bf16_f32 v37, v226, v227
	global_store_dwordx2 v173, v[60:61], s[0:1] offset:32
	v_add_u32_e32 v175, 0x2c00, v173
	global_store_dwordx2 v175, v[52:53], s[0:1] offset:32
	v_add_u32_e32 v175, 0x5800, v173
	global_store_dwordx2 v175, v[44:45], s[0:1] offset:32
	v_add_u32_e32 v175, 0x8400, v173
	global_store_dwordx2 v175, v[36:37], s[0:1] offset:32
	v_mov_b32_dpp v216, v0 row_shr:1 row_mask:0xf bank_mask:0xf bound_ctrl:1
	v_mov_b32_dpp v217, v1 row_shr:1 row_mask:0xf bank_mask:0xf bound_ctrl:1
	v_mov_b32_dpp v218, v2 row_shr:1 row_mask:0xf bank_mask:0xf bound_ctrl:1
	v_mov_b32_dpp v219, v3 row_shr:1 row_mask:0xf bank_mask:0xf bound_ctrl:1
	v_mov_b32_dpp v220, v24 row_shl:1 row_mask:0xf bank_mask:0xf bound_ctrl:1
	v_mov_b32_dpp v221, v25 row_shl:1 row_mask:0xf bank_mask:0xf bound_ctrl:1
	v_mov_b32_dpp v222, v26 row_shl:1 row_mask:0xf bank_mask:0xf bound_ctrl:1
	v_mov_b32_dpp v223, v27 row_shl:1 row_mask:0xf bank_mask:0xf bound_ctrl:1
	v_pk_mul_f32 v[176:177], v[24:25], v[132:133]
	v_pk_mul_f32 v[178:179], v[26:27], v[134:135]
	v_pk_mul_f32 v[180:181], v[16:17], v[132:133]
	v_pk_mul_f32 v[182:183], v[18:19], v[134:135]
	v_pk_mul_f32 v[184:185], v[8:9], v[132:133]
	v_pk_mul_f32 v[186:187], v[10:11], v[134:135]
	v_pk_mul_f32 v[224:225], v[0:1], v[132:133]
	v_pk_mul_f32 v[226:227], v[2:3], v[134:135]
	v_pk_fma_f32 v[176:177], v[128:129], v[216:217], v[176:177]
	v_pk_fma_f32 v[178:179], v[130:131], v[218:219], v[178:179]
	v_pk_fma_f32 v[180:181], v[128:129], v[24:25], v[180:181]
	v_pk_fma_f32 v[182:183], v[130:131], v[26:27], v[182:183]
	v_pk_fma_f32 v[184:185], v[128:129], v[16:17], v[184:185]
	v_pk_fma_f32 v[186:187], v[130:131], v[18:19], v[186:187]
	v_pk_fma_f32 v[224:225], v[128:129], v[8:9], v[224:225]
	v_pk_fma_f32 v[226:227], v[130:131], v[10:11], v[226:227]
	v_pk_fma_f32 v[176:177], v[136:137], v[16:17], v[176:177]
	v_pk_fma_f32 v[178:179], v[138:139], v[18:19], v[178:179]
	v_pk_fma_f32 v[180:181], v[136:137], v[8:9], v[180:181]
	v_pk_fma_f32 v[182:183], v[138:139], v[10:11], v[182:183]
	v_pk_fma_f32 v[184:185], v[136:137], v[0:1], v[184:185]
	v_pk_fma_f32 v[186:187], v[138:139], v[2:3], v[186:187]
	v_pk_fma_f32 v[224:225], v[136:137], v[220:221], v[224:225]
	v_pk_fma_f32 v[226:227], v[138:139], v[222:223], v[226:227]
	v_pk_add_f32 v[176:177], v[140:141], v[176:177]
	v_pk_add_f32 v[178:179], v[142:143], v[178:179]
	v_pk_add_f32 v[180:181], v[140:141], v[180:181]
	v_pk_add_f32 v[182:183], v[142:143], v[182:183]
	v_pk_add_f32 v[184:185], v[140:141], v[184:185]
	v_pk_add_f32 v[186:187], v[142:143], v[186:187]
	v_pk_add_f32 v[224:225], v[140:141], v[224:225]
	v_pk_add_f32 v[226:227], v[142:143], v[226:227]
	v_mov_b32_dpp v216, v4 row_shr:1 row_mask:0xf bank_mask:0xf bound_ctrl:1
	v_mov_b32_dpp v217, v5 row_shr:1 row_mask:0xf bank_mask:0xf bound_ctrl:1
	v_mov_b32_dpp v218, v6 row_shr:1 row_mask:0xf bank_mask:0xf bound_ctrl:1
	v_mov_b32_dpp v219, v7 row_shr:1 row_mask:0xf bank_mask:0xf bound_ctrl:1
	v_mov_b32_dpp v220, v28 row_shl:1 row_mask:0xf bank_mask:0xf bound_ctrl:1
	v_mov_b32_dpp v221, v29 row_shl:1 row_mask:0xf bank_mask:0xf bound_ctrl:1
	v_mov_b32_dpp v222, v30 row_shl:1 row_mask:0xf bank_mask:0xf bound_ctrl:1
	v_mov_b32_dpp v223, v31 row_shl:1 row_mask:0xf bank_mask:0xf bound_ctrl:1
	v_pk_mul_f32 v[24:25], v[28:29], v[148:149]
	v_pk_mul_f32 v[26:27], v[30:31], v[150:151]
	v_pk_mul_f32 v[16:17], v[20:21], v[148:149]
; __device__ __forceinline__ void st_bf4(bf16_t* p, f32x4 v) { u32x2 w; w.x = pk2(v[0], v[1]); w.y = pk2(v[2], v[3]); *(u32x2*)p = w; }
; __device__ __forceinline__ float sigmoidf_(float x) { return __builtin_amdgcn_rcpf(1.f + __expf(-x)); }
; __device__ __forceinline__ float dpp_ror1(float v) { return __int_as_float(__builtin_amdgcn_update_dpp(0, __float_as_int(v), 0x121, 0xf, 0xf, false)); }
; __device__ __forceinline__ float dpp_rol1(float v) { return __int_as_float(__builtin_amdgcn_update_dpp(0, __float_as_int(v), 0x12F, 0xf, 0xf, false)); }
;     __device__ __forceinline__ void tile(const f32x4 (&acc)[2][2][4][2], const Unit& u, int wr, int wc, int fr, int fq) const {
;     ...
;             const int cv = 128 * u.pn + 32 * wc + 16 * n + 4 * fq, cg = FF + cv;
;             const f32x4 wv0 = *(const f32x4*)(cw + cv), wv1 = *(const f32x4*)(cw + F2 + cv), wv2 = *(const f32x4*)(cw + 2 * F2 + cv), bv = *(const f32x4*)(cb + cv);
;             const f32x4 wg0 = *(const f32x4*)(cw + cg), wg1 = *(const f32x4*)(cw + F2 + cg), wg2 = *(const f32x4*)(cw + 2 * F2 + cg), bg = *(const f32x4*)(cb + cg);
;     ...
;                     for (int i = 0; i < 4; ++i) {
;                         const float xv = acc[ai][0][m][n][i], xg = acc[ai][1][m][n][i];
;                         const float uv = m > 0 ? acc[ai][0][m > 0 ? m - 1 : 0][n][i] : 0.f, ug = m > 0 ? acc[ai][1][m > 0 ? m - 1 : 0][n][i] : 0.f;
;                         const float dv = m < 3 ? acc[ai][0][m < 3 ? m + 1 : 3][n][i] : 0.f, dg = m < 3 ? acc[ai][1][m < 3 ? m + 1 : 3][n][i] : 0.f;
;                         const float pv = dpp_ror1(fr == 15 ? uv : xv), pg = dpp_ror1(fr == 15 ? ug : xg);
;                         const float nv = dpp_rol1(fr == 0 ? dv : xv), ng = dpp_rol1(fr == 0 ? dg : xg);
;                         const float yv = wv0[i] * pv + wv1[i] * xv + wv2[i] * nv + bv[i];
;                         const float yg = wg0[i] * pg + wg1[i] * xg + wg2[i] * ng + bg[i];
;                         r[i] = yg * sigmoidf_(yg) * yv;
;                     }
;                     st_bf4(ACT + (size_t)(u.pm * BM + ai * HALF + wr * 64 + m * 16 + fr) * FF + cv, r);
	v_pk_mul_f32 v[18:19], v[22:23], v[150:151]
	v_pk_mul_f32 v[8:9], v[12:13], v[148:149]
	v_pk_mul_f32 v[10:11], v[14:15], v[150:151]
	v_pk_mul_f32 v[0:1], v[4:5], v[148:149]
	v_pk_mul_f32 v[2:3], v[6:7], v[150:151]
	v_pk_fma_f32 v[24:25], v[144:145], v[216:217], v[24:25]
	v_pk_fma_f32 v[26:27], v[146:147], v[218:219], v[26:27]
	v_pk_fma_f32 v[16:17], v[144:145], v[28:29], v[16:17]
	v_pk_fma_f32 v[18:19], v[146:147], v[30:31], v[18:19]
	v_pk_fma_f32 v[8:9], v[144:145], v[20:21], v[8:9]
	v_pk_fma_f32 v[10:11], v[146:147], v[22:23], v[10:11]
	v_pk_fma_f32 v[0:1], v[144:145], v[12:13], v[0:1]
	v_pk_fma_f32 v[2:3], v[146:147], v[14:15], v[2:3]
	v_pk_fma_f32 v[24:25], v[208:209], v[20:21], v[24:25]
	v_pk_fma_f32 v[26:27], v[210:211], v[22:23], v[26:27]
	v_pk_fma_f32 v[16:17], v[208:209], v[12:13], v[16:17]
	v_pk_fma_f32 v[18:19], v[210:211], v[14:15], v[18:19]
	v_pk_fma_f32 v[8:9], v[208:209], v[4:5], v[8:9]
	v_pk_fma_f32 v[10:11], v[210:211], v[6:7], v[10:11]
	v_pk_fma_f32 v[0:1], v[208:209], v[220:221], v[0:1]
	v_pk_fma_f32 v[2:3], v[210:211], v[222:223], v[2:3]
	v_pk_add_f32 v[24:25], v[212:213], v[24:25]
	v_pk_add_f32 v[26:27], v[214:215], v[26:27]
	v_pk_add_f32 v[16:17], v[212:213], v[16:17]
	v_pk_add_f32 v[18:19], v[214:215], v[18:19]
	v_pk_add_f32 v[8:9], v[212:213], v[8:9]
	v_pk_add_f32 v[10:11], v[214:215], v[10:11]
	v_pk_add_f32 v[0:1], v[212:213], v[0:1]
	v_pk_add_f32 v[2:3], v[214:215], v[2:3]
	v_mul_f32_e32 v28, 0xbfb8aa3b, v176
	v_mul_f32_e32 v29, 0xbfb8aa3b, v177
	v_mul_f32_e32 v30, 0xbfb8aa3b, v178
	v_mul_f32_e32 v31, 0xbfb8aa3b, v179
	v_mul_f32_e32 v20, 0xbfb8aa3b, v180
	v_mul_f32_e32 v21, 0xbfb8aa3b, v181
	v_mul_f32_e32 v22, 0xbfb8aa3b, v182
	v_mul_f32_e32 v23, 0xbfb8aa3b, v183
	v_mul_f32_e32 v12, 0xbfb8aa3b, v184
	v_mul_f32_e32 v13, 0xbfb8aa3b, v185
	v_mul_f32_e32 v14, 0xbfb8aa3b, v186
	v_mul_f32_e32 v15, 0xbfb8aa3b, v187
	v_mul_f32_e32 v4, 0xbfb8aa3b, v224
	v_mul_f32_e32 v5, 0xbfb8aa3b, v225
	v_mul_f32_e32 v6, 0xbfb8aa3b, v226
	v_mul_f32_e32 v7, 0xbfb8aa3b, v227
	v_exp_f32_e32 v28, v28
	v_exp_f32_e32 v29, v29
	v_exp_f32_e32 v30, v30
	v_exp_f32_e32 v31, v31
	v_exp_f32_e32 v20, v20
	v_exp_f32_e32 v21, v21
	v_exp_f32_e32 v22, v22
	v_exp_f32_e32 v23, v23
	v_exp_f32_e32 v12, v12
	v_exp_f32_e32 v13, v13
	v_exp_f32_e32 v14, v14
	v_exp_f32_e32 v15, v15
	v_exp_f32_e32 v4, v4
	v_exp_f32_e32 v5, v5
	v_exp_f32_e32 v6, v6
	v_exp_f32_e32 v7, v7
	v_add_f32_e32 v28, 1.0, v28
	v_add_f32_e32 v29, 1.0, v29
	v_add_f32_e32 v30, 1.0, v30
	v_add_f32_e32 v31, 1.0, v31
	v_add_f32_e32 v20, 1.0, v20
	v_add_f32_e32 v21, 1.0, v21
	v_add_f32_e32 v22, 1.0, v22
	v_add_f32_e32 v23, 1.0, v23
	v_add_f32_e32 v12, 1.0, v12
	v_add_f32_e32 v13, 1.0, v13
	v_add_f32_e32 v14, 1.0, v14
	v_add_f32_e32 v15, 1.0, v15
	v_add_f32_e32 v4, 1.0, v4
	v_add_f32_e32 v5, 1.0, v5
	v_add_f32_e32 v6, 1.0, v6
	v_add_f32_e32 v7, 1.0, v7
	v_rcp_f32_e32 v28, v28
	v_rcp_f32_e32 v29, v29
	v_rcp_f32_e32 v30, v30
	v_rcp_f32_e32 v31, v31
	v_rcp_f32_e32 v20, v20
	v_rcp_f32_e32 v21, v21
	v_rcp_f32_e32 v22, v22
	v_rcp_f32_e32 v23, v23
	v_rcp_f32_e32 v12, v12
	v_rcp_f32_e32 v13, v13
	v_rcp_f32_e32 v14, v14
	v_rcp_f32_e32 v15, v15
	v_rcp_f32_e32 v4, v4
	v_rcp_f32_e32 v5, v5
	v_rcp_f32_e32 v6, v6
	v_rcp_f32_e32 v7, v7
	v_pk_mul_f32 v[176:177], v[176:177], v[28:29]
	v_pk_mul_f32 v[178:179], v[178:179], v[30:31]
	v_pk_mul_f32 v[180:181], v[180:181], v[20:21]
	v_pk_mul_f32 v[182:183], v[182:183], v[22:23]
	v_pk_mul_f32 v[184:185], v[184:185], v[12:13]
	v_pk_mul_f32 v[186:187], v[186:187], v[14:15]
	v_pk_mul_f32 v[224:225], v[224:225], v[4:5]
	v_pk_mul_f32 v[226:227], v[226:227], v[6:7]
	v_pk_mul_f32 v[176:177], v[24:25], v[176:177]
	v_pk_mul_f32 v[178:179], v[26:27], v[178:179]
	v_pk_mul_f32 v[180:181], v[16:17], v[180:181]
	v_pk_mul_f32 v[182:183], v[18:19], v[182:183]
	v_pk_mul_f32 v[184:185], v[8:9], v[184:185]
	v_pk_mul_f32 v[186:187], v[10:11], v[186:187]
	v_pk_mul_f32 v[224:225], v[0:1], v[224:225]
	v_pk_mul_f32 v[226:227], v[2:3], v[226:227]
	v_cvt_pk_bf16_f32 v28, v176, v177
	v_cvt_pk_bf16_f32 v29, v178, v179
	v_cvt_pk_bf16_f32 v20, v180, v181
	v_cvt_pk_bf16_f32 v21, v182, v183
	v_cvt_pk_bf16_f32 v12, v184, v185
	v_cvt_pk_bf16_f32 v13, v186, v187
	v_cvt_pk_bf16_f32 v4, v224, v225
	v_cvt_pk_bf16_f32 v5, v226, v227
	global_store_dwordx2 v174, v[28:29], s[0:1] offset:32
	v_add_u32_e32 v175, 0x2c00, v174
	global_store_dwordx2 v175, v[20:21], s[0:1] offset:32
	v_add_u32_e32 v175, 0x5800, v174
	global_store_dwordx2 v175, v[12:13], s[0:1] offset:32
	v_add_u32_e32 v175, 0x8400, v174
	global_store_dwordx2 v175, v[4:5], s[0:1] offset:32
	v_lshl_or_b32 v170, s16, 7, v204
	v_lshlrev_b32_e32 v171, 2, v170
	v_add_u32_e32 v172, 0x5800, v171
	global_load_dwordx4 v[230:233], v172, s[56:57]
	global_load_dwordx4 v[234:237], v172, s[12:13]
	global_load_dwordx4 v[238:241], v172, s[14:15]
	global_load_dwordx4 v[242:245], v172, s[58:59]
	global_load_dwordx4 v[246:249], v171, s[56:57]
	global_load_dwordx4 v[250:253], v171, s[12:13]
	s_mov_b32 s98, 1
	s_andn2_b64 vcc, exec, s[20:21]
	s_mov_b64 s[20:21], -1
	s_cbranch_vccnz .LBB0_1795
	s_andn2_b64 vcc, exec, s[2:3]
	s_cbranch_vccnz .LBB0_1794
	s_barrier
	s_branch .LBB0_1794
